# M1 delta-C stage: all fragment reads first, 16 MFMAs back to back, then converts/writes (was one tile at a time)
# baseline (speedup 1.0000x reference)
.LBB0_360:
	s_or_b64 exec, exec, s[0:1]
	v_ashrrev_i32_e32 v38, 2, v2
	v_lshrrev_b32_e32 v35, 1, v2
	v_bfi_b32 v34, -16, v38, v2
	v_and_b32_e32 v42, 24, v35
	v_mul_lo_u32 v34, v34, s36
	v_lshlrev_b32_e32 v35, 1, v42
	v_and_b32_e32 v3, 15, v2
	v_add3_u32 v34, 0, v34, v35
	ds_read_b128 v[130:133], v34
	ds_read_b128 v[134:137], v34 offset:64
	v_mul_u32_u24_e32 v34, 0x90, v3
	v_add3_u32 v110, 0, v34, v35
	ds_read_b128 v[138:141], v110 offset:18432
	ds_read_b128 v[142:145], v110 offset:18496
	ds_read_b128 v[146:149], v110 offset:20736
	ds_read_b128 v[150:153], v110 offset:20800
	ds_read_b128 v[154:157], v110 offset:23040
	ds_read_b128 v[158:161], v110 offset:23104
	ds_read_b128 v[162:165], v110 offset:25344
	ds_read_b128 v[166:169], v110 offset:25408
	ds_read_b128 v[170:173], v110 offset:27648
	ds_read_b128 v[174:177], v110 offset:27712
	ds_read_b128 v[178:181], v110 offset:29952
	ds_read_b128 v[182:185], v110 offset:30016
	ds_read_b128 v[186:189], v110 offset:32256
	ds_read_b128 v[190:193], v110 offset:32320
	ds_read_b128 v[194:197], v110 offset:34560
	ds_read_b128 v[198:201], v110 offset:34624
	v_and_b32_e32 v43, -16, v38
	v_lshl_add_u32 v43, v43, 1, s41
	v_mul_u32_u24_e32 v3, 0x110, v3
	v_add3_u32 v111, v43, v42, v3
	s_waitcnt lgkmcnt(15)
	v_mfma_f32_16x16x32_bf16 v[138:141], v[130:133], v[138:141], 0
	s_waitcnt lgkmcnt(13)
	v_mfma_f32_16x16x32_bf16 v[146:149], v[130:133], v[146:149], 0
	s_waitcnt lgkmcnt(11)
	v_mfma_f32_16x16x32_bf16 v[154:157], v[130:133], v[154:157], 0
	s_waitcnt lgkmcnt(9)
	v_mfma_f32_16x16x32_bf16 v[162:165], v[130:133], v[162:165], 0
	s_waitcnt lgkmcnt(7)
	v_mfma_f32_16x16x32_bf16 v[170:173], v[130:133], v[170:173], 0
	s_waitcnt lgkmcnt(5)
	v_mfma_f32_16x16x32_bf16 v[178:181], v[130:133], v[178:181], 0
	s_waitcnt lgkmcnt(3)
	v_mfma_f32_16x16x32_bf16 v[186:189], v[130:133], v[186:189], 0
	s_waitcnt lgkmcnt(1)
	v_mfma_f32_16x16x32_bf16 v[194:197], v[130:133], v[194:197], 0
	s_waitcnt lgkmcnt(0)
	v_mfma_f32_16x16x32_bf16 v[138:141], v[134:137], v[142:145], v[138:141]
	v_mfma_f32_16x16x32_bf16 v[146:149], v[134:137], v[150:153], v[146:149]
	v_mfma_f32_16x16x32_bf16 v[154:157], v[134:137], v[158:161], v[154:157]
	v_mfma_f32_16x16x32_bf16 v[162:165], v[134:137], v[166:169], v[162:165]
	v_mfma_f32_16x16x32_bf16 v[170:173], v[134:137], v[174:177], v[170:173]
	v_mfma_f32_16x16x32_bf16 v[178:181], v[134:137], v[182:185], v[178:181]
	v_mfma_f32_16x16x32_bf16 v[186:189], v[134:137], v[190:193], v[186:189]
	v_mfma_f32_16x16x32_bf16 v[194:197], v[134:137], v[198:201], v[194:197]
	v_cvt_pk_bf16_f32 v142, v138, v139
	v_cvt_pk_bf16_f32 v143, v140, v141
	ds_write_b64 v111, v[142:143]
	v_cvt_pk_bf16_f32 v150, v146, v147
	v_cvt_pk_bf16_f32 v151, v148, v149
	ds_write_b64 v111, v[150:151] offset:4352
	v_cvt_pk_bf16_f32 v158, v154, v155
	v_cvt_pk_bf16_f32 v159, v156, v157
	ds_write_b64 v111, v[158:159] offset:8704
	v_cvt_pk_bf16_f32 v166, v162, v163
	v_cvt_pk_bf16_f32 v167, v164, v165
	ds_write_b64 v111, v[166:167] offset:13056
	v_cvt_pk_bf16_f32 v174, v170, v171
	v_cvt_pk_bf16_f32 v175, v172, v173
	ds_write_b64 v111, v[174:175] offset:17408
	v_cvt_pk_bf16_f32 v182, v178, v179
	v_cvt_pk_bf16_f32 v183, v180, v181
	ds_write_b64 v111, v[182:183] offset:21760
	v_cvt_pk_bf16_f32 v190, v186, v187
	v_cvt_pk_bf16_f32 v191, v188, v189
	ds_write_b64 v111, v[190:191] offset:26112
	v_cvt_pk_bf16_f32 v198, v194, v195
	v_cvt_pk_bf16_f32 v199, v196, v197
	ds_write_b64 v111, v[198:199] offset:30464
	v_lshlrev_b64 v[62:63], 15, v[32:33]
	v_lshlrev_b32_e32 v98, 1, v85
	v_add_u32_e32 v85, 0x200, v2
	v_add_u32_e32 v102, 0x400, v2
	v_add_u32_e32 v103, 0x600, v2
	s_nop 2
	v_mov_b32_e32 v99, v0
	v_lshlrev_b32_e32 v100, 7, v84
	v_ashrrev_i32_e32 v106, 4, v102
	v_ashrrev_i32_e32 v103, 4, v103
	s_add_u32 s22, s22, s12
	s_addc_u32 s23, s23, s13
	v_ashrrev_i32_e32 v101, 31, v100
	s_add_i32 s20, s20, s40
	s_nop 2
	v_lshlrev_b32_e32 v108, 7, v103
	s_add_u32 s24, s24, s26
	v_ashrrev_i32_e32 v109, 31, v108
	s_waitcnt vmcnt(2)
	v_mov_b64_e32 v[34:35], v[30:31]
	v_mov_b64_e32 v[38:39], v[26:27]
	v_mov_b64_e32 v[46:47], v[22:23]
	v_mov_b64_e32 v[54:55], v[18:19]
	v_mov_b64_e32 v[50:51], v[14:15]
	s_nop 1
	v_lshl_add_u64 v[2:3], s[80:81], 0, v[62:63]
	v_add_u32_e32 v62, s41, v98
	v_ashrrev_i32_e32 v63, 4, v85
	v_mad_u64_u32 v[84:85], s[0:1], v84, s37, v[62:63]
	v_lshl_add_u64 v[2:3], v[2:3], 0, v[98:99]
	v_mad_u64_u32 v[98:99], s[0:1], v63, s37, v[62:63]
	v_lshlrev_b32_e32 v102, 7, v63
	s_nop 3
	v_mad_u64_u32 v[104:105], s[0:1], v106, s37, v[62:63]
	v_mad_u64_u32 v[62:63], s[0:1], v103, s37, v[62:63]
	v_lshlrev_b32_e32 v106, 7, v106
	v_lshl_add_u64 v[100:101], v[100:101], 1, v[2:3]
	v_ashrrev_i32_e32 v103, 31, v102
	v_ashrrev_i32_e32 v107, 31, v106
	v_mov_b64_e32 v[42:43], v[6:7]
	s_nop 2
	s_addc_u32 s25, s25, s27
	v_lshl_add_u64 v[102:103], v[102:103], 1, v[2:3]
	v_lshl_add_u64 v[106:107], v[106:107], 1, v[2:3]
	v_lshl_add_u64 v[2:3], v[108:109], 1, v[2:3]
	s_waitcnt vmcnt(0)
	v_mov_b32_e32 v60, v65
	v_mov_b32_e32 v61, v1
	v_mov_b64_e32 v[32:33], v[28:29]
	v_mov_b64_e32 v[36:37], v[24:25]
	s_nop 1
	v_mov_b64_e32 v[44:45], v[20:21]
	v_mov_b64_e32 v[52:53], v[16:17]
	v_mov_b64_e32 v[48:49], v[12:13]
	v_mov_b64_e32 v[40:41], v[4:5]
	s_cmpk_lt_i32 s22, 0x800
	s_nop 5
	s_nop 7
	s_waitcnt lgkmcnt(0)
	s_barrier
	ds_read_b128 v[56:59], v84
	ds_read_b128 v[84:87], v98
	ds_read_b128 v[88:91], v104
	ds_read_b128 v[92:95], v62
	s_waitcnt lgkmcnt(3)
	global_store_dwordx4 v[100:101], v[56:59], off
	s_waitcnt lgkmcnt(2)
	global_store_dwordx4 v[102:103], v[84:87], off
	s_waitcnt lgkmcnt(1)
	global_store_dwordx4 v[106:107], v[88:91], off
	s_waitcnt lgkmcnt(0)
	global_store_dwordx4 v[2:3], v[92:95], off
	v_mov_b64_e32 v[58:59], v[10:11]
	v_mov_b64_e32 v[56:57], v[8:9]
	s_cbranch_scc0 .LBB0_378
